# gating: the next unit's stats, VG and U rows are fetched one whole unit ahead into a register buffer and copied into place; first-unit wait moved to the preamble
# baseline (speedup 1.0000x reference)
; __device__ __forceinline__ void gate_phase(int bx, int G, bool skip_ctx, const bf16* __restrict__ VG, const bf16* __restrict__ U, const float* __restrict__ stats, ...
;     ...
;     auto unit_ok = [&](int u) { return u < NU && !(skip_ctx && ((u >> 3) % 34) < 2); };
;     auto next_unit = [&](int u) { u += G; while (u < NU && !unit_ok(u)) u += G; return u; };
;     int u = bx; if (!unit_ok(u)) u = next_unit(u);
;     GateRegs R;
;     ...
;     if (u < NU) GATE_LOAD(u);
;     ...
;         const float bias = bsl[h * 128 + p];
;         const int un = next_unit(u);
;         if (un < NU) GATE_LOAD(un);
.LBB0_39:
	s_cmpk_gt_i32 s3, 0x87f
	s_cbranch_scc1 .LBB0_51
	s_lshl_b32 s22, s12, 9
	s_ashr_i32 s23, s22, 31
	s_lshl_b64 s[26:27], s[22:23], 2
	s_waitcnt lgkmcnt(0)
	s_add_u32 s22, s8, s26
	s_addc_u32 s23, s9, s27
	s_add_u32 s26, s10, s26
	s_addc_u32 s27, s11, s27
	s_ashr_i32 s13, s12, 31
	s_lshl_b64 s[8:9], s[12:13], 18
	s_add_u32 s8, s28, s8
	s_addc_u32 s9, s29, s9
	s_add_u32 s38, s8, 0x5800000
	s_addc_u32 s39, s9, 0
	s_lshl_b32 s8, s12, 10
	s_ashr_i32 s9, s8, 31
	s_lshl_b64 s[8:9], s[8:9], 2
	s_add_u32 s6, s6, s8
	s_addc_u32 s7, s7, s9
	v_ashrrev_i32_e32 v100, 2, v4
	s_movk_i32 s8, 0xffe0
	v_bfi_b32 v102, s8, v100, v4
	s_add_u32 s8, s28, 0x11efa000
	s_addc_u32 s9, s29, 0
	s_add_u32 s10, s28, 0x140fa000
	s_addc_u32 s11, s29, 0
	s_ashr_i32 s46, s3, 3
	s_ashr_i32 s47, s46, 31
	v_lshlrev_b32_e32 v0, 4, v4
	s_lshl_b64 s[46:47], s[46:47], 7
	v_ashrrev_i32_e32 v101, 31, v100
	v_and_b32_e32 v6, 48, v0
	v_lshl_add_u64 v[0:1], s[46:47], 0, v[100:101]
	s_and_b32 s13, s3, 7
	v_lshlrev_b64 v[2:3], 6, v[0:1]
	v_lshlrev_b64 v[0:1], 10, v[0:1]
	v_lshl_add_u64 v[0:1], s[10:11], 0, v[0:1]
	s_lshl_b32 s72, s13, 7
	v_lshl_add_u64 v[0:1], v[0:1], 0, s[72:73]
	v_lshlrev_b32_e32 v160, 1, v6
	v_lshl_add_u64 v[2:3], s[40:41], 0, v[2:3]
	v_lshl_add_u64 v[0:1], v[0:1], 0, v[160:161]
	v_ashrrev_i32_e32 v103, 31, v102
	global_load_dwordx4 v[16:19], v[2:3], off offset:48
	global_load_dwordx4 v[20:23], v[2:3], off offset:32
	global_load_dwordx4 v[24:27], v[2:3], off offset:16
	global_load_dwordx4 v[28:31], v[2:3], off
	global_load_dwordx4 v[32:35], v[0:1], off offset:16 nt
	global_load_dwordx4 v[36:39], v[0:1], off nt
	v_lshl_add_u64 v[0:1], s[46:47], 0, v[102:103]
	v_lshlrev_b64 v[0:1], 10, v[0:1]
	v_lshrrev_b32_e32 v2, 1, v4
	v_lshl_add_u64 v[0:1], s[8:9], 0, v[0:1]
	v_and_b32_e32 v8, 32, v2
	v_bfe_u32 v5, v4, 5, 1
	v_lshl_add_u64 v[0:1], v[0:1], 0, s[72:73]
	v_lshlrev_b32_e32 v160, 1, v8
	v_lshl_add_u64 v[0:1], v[0:1], 0, v[160:161]
	v_lshlrev_b32_e32 v160, 3, v5
	v_lshl_add_u64 v[0:1], v[0:1], 0, v[160:161]
	global_load_dwordx2 v[124:125], v[0:1], off nt
	global_load_dwordx2 v[122:123], v[0:1], off offset:16 nt
	global_load_dwordx2 v[120:121], v[0:1], off offset:32 nt
	global_load_dwordx2 v[106:107], v[0:1], off offset:48 nt
	v_lshl_add_u64 v[0:1], s[72:73], 0, v[102:103]
	v_lshlrev_b64 v[0:1], 8, v[0:1]
	v_lshl_add_u64 v[0:1], s[38:39], 0, v[0:1]
	v_lshlrev_b32_e32 v160, 4, v5
	v_lshl_add_u64 v[10:11], v[0:1], 0, v[160:161]
	global_load_dwordx4 v[0:3], v[10:11], off
	global_load_dwordx4 v[60:63], v[10:11], off offset:32
	global_load_dwordx4 v[64:67], v[10:11], off offset:64
	global_load_dwordx4 v[52:55], v[10:11], off offset:96
	global_load_dwordx4 v[56:59], v[10:11], off offset:128
	global_load_dwordx4 v[48:51], v[10:11], off offset:160
	global_load_dwordx4 v[44:47], v[10:11], off offset:192
	global_load_dwordx4 v[40:43], v[10:11], off offset:224
	v_lshlrev_b32_e32 v10, 2, v5
	v_lshlrev_b32_e32 v12, 2, v6
	v_mov_b32_e32 v13, v161
	v_and_or_b32 v4, v4, 31, v8
	s_movk_i32 s13, 0x110
	v_mul_u32_u24_e32 v9, 0x88, v6
	v_lshl_add_u64 v[104:105], s[22:23], 0, v[12:13]
	v_lshl_add_u64 v[108:109], s[26:27], 0, v[12:13]
	v_lshlrev_b32_e32 v5, 1, v100
	v_mad_u32_u24 v7, v4, s13, 0
	v_or_b32_e32 v4, v10, v8
	v_lshlrev_b64 v[12:13], 11, v[102:103]
	v_lshlrev_b32_e32 v9, 1, v9
	v_lshl_add_u64 v[110:111], s[38:39], 0, v[160:161]
	v_lshl_add_u64 v[112:113], s[16:17], 0, v[12:13]
	v_add3_u32 v134, 0, v5, v9
	v_add3_u32 v135, 0, v9, v5
	v_lshlrev_b32_e32 v114, 1, v6
	v_lshlrev_b32_e32 v116, 1, v8
	v_lshlrev_b32_e32 v118, 1, v10
	v_add_u32_e32 v136, v7, v160
	v_lshlrev_b32_e32 v160, 1, v4
	s_and_b32 s37, s3, 7
	s_lshl_b32 s38, s37, 8
	s_mov_b32 s39, 0
	v_lshl_add_u64 v[252:253], v[104:105], 0, s[38:39]
	global_load_dwordx4 v[218:221], v[252:253], off
	global_load_dwordx4 v[222:225], v[252:253], off offset:16
	global_load_dwordx4 v[226:229], v[252:253], off offset:32
	global_load_dwordx4 v[230:233], v[252:253], off offset:48
	v_lshl_add_u64 v[252:253], v[108:109], 0, s[38:39]
	global_load_dwordx4 v[234:237], v[252:253], off
	global_load_dwordx4 v[238:241], v[252:253], off offset:16
	global_load_dwordx4 v[242:245], v[252:253], off offset:32
	global_load_dwordx4 v[246:249], v[252:253], off offset:48
	v_lshl_add_u32 v252, s37, 7, v102
	v_ashrrev_i32_e32 v253, 31, v252
	v_lshl_add_u64 v[252:253], v[252:253], 2, s[6:7]
	global_load_dword v137, v[252:253], off
	s_add_i32 s37, s3, s24
.Lgate_n1_chk:
	s_cmpk_gt_i32 s37, 0x87f
	s_cbranch_scc1 .Lgate_n1_none
	s_ashr_i32 s26, s37, 3
	s_mul_hi_i32 s38, s26, 0x78787879
	s_lshr_b32 s39, s38, 31
	s_ashr_i32 s38, s38, 4
	s_add_i32 s38, s38, s39
	s_mul_i32 s38, s38, 34
	s_sub_i32 s38, s26, s38
	s_cmp_gt_i32 s38, 1
	s_cselect_b64 s[38:39], -1, 0
	s_xor_b64 s[22:23], s[20:21], -1
	s_or_b64 s[38:39], s[22:23], s[38:39]
	s_and_b64 vcc, exec, s[38:39]
	s_cbranch_vccnz .Lgate_n1_ok
	s_add_i32 s37, s37, s24
	s_branch .Lgate_n1_chk
.Lgate_n1_ok:
	s_ashr_i32 s27, s26, 31
	s_lshl_b64 s[22:23], s[26:27], 7
	v_lshl_add_u64 v[4:5], s[22:23], 0, v[100:101]
	s_and_b32 s25, s37, 7
	v_lshlrev_b64 v[6:7], 6, v[4:5]
	v_lshlrev_b64 v[4:5], 10, v[4:5]
	v_lshl_add_u64 v[4:5], s[10:11], 0, v[4:5]
	s_lshl_b32 s72, s25, 7
	v_lshl_add_u64 v[4:5], v[4:5], 0, s[72:73]
	v_mov_b32_e32 v115, v161
	v_lshl_add_u64 v[6:7], s[40:41], 0, v[6:7]
	v_lshl_add_u64 v[4:5], v[4:5], 0, v[114:115]
	global_load_dwordx4 v[172:175], v[6:7], off offset:48
	global_load_dwordx4 v[176:179], v[6:7], off offset:32
	global_load_dwordx4 v[180:183], v[6:7], off offset:16
	global_load_dwordx4 v[184:187], v[6:7], off
	global_load_dwordx4 v[188:191], v[4:5], off offset:16 nt
	global_load_dwordx4 v[192:195], v[4:5], off nt
	v_lshl_add_u64 v[4:5], s[22:23], 0, v[102:103]
	v_lshlrev_b64 v[4:5], 10, v[4:5]
	v_lshl_add_u64 v[4:5], s[8:9], 0, v[4:5]
	v_lshl_add_u64 v[4:5], v[4:5], 0, s[72:73]
	v_mov_b32_e32 v117, v161
	v_lshl_add_u64 v[4:5], v[4:5], 0, v[116:117]
	v_mov_b32_e32 v119, v161
	v_lshl_add_u64 v[4:5], v[4:5], 0, v[118:119]
	global_load_dwordx2 v[196:197], v[4:5], off nt
	global_load_dwordx2 v[198:199], v[4:5], off offset:16 nt
	global_load_dwordx2 v[164:165], v[4:5], off offset:32 nt
	global_load_dwordx2 v[166:167], v[4:5], off offset:48 nt
	global_load_dword v250, v[252:253], off
	global_load_dword v250, v[252:253], off
	global_load_dword v250, v[252:253], off
	global_load_dword v250, v[252:253], off
	s_waitcnt vmcnt(14)
	s_branch .LBB0_45
.Lgate_n1_none:
	s_waitcnt vmcnt(0)
	s_branch .LBB0_45

; __device__ __forceinline__ unsigned pk2(float lo, float hi) { return pg8::cvt_pk_bf16(lo, hi); }
; __device__ __forceinline__ float bflo(unsigned w) { return __uint_as_float(w << 16); }
; __device__ __forceinline__ float bfhi(unsigned w) { return __uint_as_float(w & 0xffff0000u); }
; __device__ __forceinline__ void gate_phase(int bx, int G, bool skip_ctx, const bf16* __restrict__ VG, const bf16* __restrict__ U, const float* __restrict__ stats, ...
;     ...
;         __syncthreads();
;         f32x16 acc = {};
;         const bf16* trow = T + (db * 32 + r32) * GT_PITCH + hi * 8;
; #pragma unroll
;         for (int ks = 0; ks < 8; ++ks) {
;             const bf16x8 av = *(const bf16x8*)(trow + ks * 16);
;             acc = __builtin_amdgcn_mfma_f32_32x32x16_bf16(av, wcur[ks], acc, 0, 0, 0);
;         }
;         const size_t row = (size_t)chunk * 128 + p;
; #pragma unroll
;         for (int g4 = 0; g4 < 4; ++g4) {
;             const int d0 = db * 32 + 8 * g4 + 4 * hi;
;             u32x2 w;
;             w.x = pk2(bflo(ucur[g4].x) * (acc[4 * g4 + 0] + bias), bfhi(ucur[g4].x) * (acc[4 * g4 + 1] + bias));
;             w.y = pk2(bflo(ucur[g4].y) * (acc[4 * g4 + 2] + bias), bfhi(ucur[g4].y) * (acc[4 * g4 + 3] + bias));
;             *(u32x2*)(MIX + row * 1024 + 512 + h * 64 + d0) = w;
;         }
;         __syncthreads();
;         u = un;
.LBB0_44:
	s_waitcnt lgkmcnt(0)
	s_barrier
	ds_read_b128 v[4:7], v136
	ds_read_b128 v[138:141], v136 offset:32
	s_waitcnt lgkmcnt(1)
	v_mfma_f32_32x32x16_bf16 v[0:15], v[4:7], v[0:3], 0
	s_ashr_i32 s26, s13, 3
	s_ashr_i32 s27, s26, 31
	s_lshl_b64 s[26:27], s[26:27], 18
	s_lshl_b32 s72, s19, 1
	s_andn2_b64 vcc, exec, s[22:23]
	s_waitcnt lgkmcnt(0)
	v_mfma_f32_32x32x16_bf16 v[0:15], v[138:141], v[60:63], v[0:15]
	ds_read_b128 v[60:63], v136 offset:64
	s_waitcnt lgkmcnt(0)
	v_mfma_f32_32x32x16_bf16 v[0:15], v[60:63], v[64:67], v[0:15]
	ds_read_b128 v[60:63], v136 offset:96
	v_mov_b64_e32 v[64:65], v[76:77]
	v_mov_b64_e32 v[66:67], v[78:79]
	s_waitcnt lgkmcnt(0)
	v_mfma_f32_32x32x16_bf16 v[0:15], v[60:63], v[52:55], v[0:15]
	ds_read_b128 v[52:55], v136 offset:128
	v_mov_b64_e32 v[60:61], v[72:73]
	v_mov_b64_e32 v[62:63], v[74:75]
	s_waitcnt lgkmcnt(0)
	v_mfma_f32_32x32x16_bf16 v[0:15], v[52:55], v[56:59], v[0:15]
	ds_read_b128 v[52:55], v136 offset:160
	v_mov_b64_e32 v[56:57], v[84:85]
	v_mov_b64_e32 v[58:59], v[86:87]
	s_waitcnt lgkmcnt(0)
	v_mfma_f32_32x32x16_bf16 v[0:15], v[52:55], v[48:51], v[0:15]
	ds_read_b128 v[48:51], v136 offset:192
	v_mov_b64_e32 v[52:53], v[80:81]
	v_mov_b64_e32 v[54:55], v[82:83]
	s_waitcnt lgkmcnt(0)
	v_mfma_f32_32x32x16_bf16 v[0:15], v[48:51], v[44:47], v[0:15]
	ds_read_b128 v[44:47], v136 offset:224
	v_mov_b64_e32 v[48:49], v[88:89]
	v_mov_b64_e32 v[50:51], v[90:91]
	s_waitcnt lgkmcnt(0)
	v_mfma_f32_32x32x16_bf16 v[0:15], v[44:47], v[40:43], v[0:15]
	v_lshlrev_b32_e32 v42, 16, v124
	v_lshl_add_u64 v[40:41], v[112:113], 0, s[26:27]
	v_lshl_add_u64 v[40:41], v[40:41], 0, s[72:73]
	v_mov_b64_e32 v[44:45], v[92:93]
	v_mov_b64_e32 v[46:47], v[94:95]
	s_nop 10
	v_add_f32_e32 v0, v137, v0
	v_mul_f32_e32 v0, v0, v42
	v_and_b32_e32 v42, 0xffff0000, v124
	v_add_f32_e32 v1, v137, v1
	v_mul_f32_e32 v1, v1, v42
	v_cvt_pk_bf16_f32 v42, v0, v1
	v_lshlrev_b32_e32 v0, 16, v125
	v_add_f32_e32 v1, v137, v2
	v_mul_f32_e32 v0, v1, v0
	v_and_b32_e32 v1, 0xffff0000, v125
	v_add_f32_e32 v2, v137, v3
	v_mul_f32_e32 v1, v2, v1
	v_lshlrev_b32_e32 v2, 16, v122
	v_add_f32_e32 v3, v137, v4
	v_mul_f32_e32 v2, v3, v2
	v_and_b32_e32 v3, 0xffff0000, v122
	v_add_f32_e32 v4, v137, v5
	v_cvt_pk_bf16_f32 v43, v0, v1
	v_lshl_add_u64 v[0:1], v[40:41], 0, v[160:161]
	v_mul_f32_e32 v3, v4, v3
	global_store_dwordx2 v[0:1], v[42:43], off offset:1024
	v_cvt_pk_bf16_f32 v2, v2, v3
	v_lshlrev_b32_e32 v3, 16, v123
	v_add_f32_e32 v4, v137, v6
	v_mul_f32_e32 v3, v4, v3
	v_and_b32_e32 v4, 0xffff0000, v123
	v_add_f32_e32 v5, v137, v7
	v_mul_f32_e32 v4, v5, v4
	v_cvt_pk_bf16_f32 v3, v3, v4
	global_store_dwordx2 v[0:1], v[2:3], off offset:1040
	v_lshlrev_b32_e32 v2, 16, v120
	v_add_f32_e32 v3, v137, v8
	v_mul_f32_e32 v2, v3, v2
	v_and_b32_e32 v3, 0xffff0000, v120
	v_add_f32_e32 v4, v137, v9
	v_mul_f32_e32 v3, v4, v3
	v_cvt_pk_bf16_f32 v2, v2, v3
	v_lshlrev_b32_e32 v3, 16, v121
	v_add_f32_e32 v4, v137, v10
	v_mul_f32_e32 v3, v4, v3
	v_and_b32_e32 v4, 0xffff0000, v121
	v_add_f32_e32 v5, v137, v11
	v_mul_f32_e32 v4, v5, v4
	v_cvt_pk_bf16_f32 v3, v3, v4
	global_store_dwordx2 v[0:1], v[2:3], off offset:1056
	v_lshlrev_b32_e32 v2, 16, v106
	v_add_f32_e32 v3, v137, v12
	v_mul_f32_e32 v2, v3, v2
	v_and_b32_e32 v3, 0xffff0000, v106
	v_add_f32_e32 v4, v137, v13
	v_mul_f32_e32 v3, v4, v3
	v_cvt_pk_bf16_f32 v2, v2, v3
	v_lshlrev_b32_e32 v3, 16, v107
	v_add_f32_e32 v4, v137, v14
	v_mul_f32_e32 v3, v4, v3
	v_and_b32_e32 v4, 0xffff0000, v107
	v_add_f32_e32 v5, v137, v15
	v_mul_f32_e32 v4, v5, v4
	v_cvt_pk_bf16_f32 v3, v3, v4
	global_store_dwordx2 v[0:1], v[2:3], off offset:1072
	v_mov_b64_e32 v[0:1], v[68:69]
	v_mov_b64_e32 v[40:41], v[96:97]
	v_mov_b64_e32 v[124:125], v[126:127]
	v_mov_b64_e32 v[122:123], v[128:129]
	v_mov_b64_e32 v[120:121], v[130:131]
	v_mov_b64_e32 v[106:107], v[132:133]
	v_mov_b64_e32 v[2:3], v[70:71]
	v_mov_b64_e32 v[42:43], v[98:99]
	s_barrier
	s_cbranch_vccnz .LBB0_51
; __device__ __forceinline__ unsigned f2bf(float f) { unsigned u = __builtin_bit_cast(unsigned, f); return (u + 0x7fffu + ((u >> 16) & 1u)) >> 16; }
; __device__ __forceinline__ float bflo(unsigned w) { return __uint_as_float(w << 16); }
; __device__ __forceinline__ float bfhi(unsigned w) { return __uint_as_float(w & 0xffff0000u); }
; __device__ __forceinline__ void gate_phase(int bx, int G, bool skip_ctx, const bf16* __restrict__ VG, const bf16* __restrict__ U, const float* __restrict__ stats, ...
;     ...
;         const int chunk = u >> 3, h = u & 7;
;         {
;             const float s1 = (R.sa[0] + R.sa[2]) + (R.sb[0] + R.sb[2]) + (R.sc[0] + R.sc[2]) + (R.sd[0] + R.sd[2]);
;             const float s2 = (R.sa[1] + R.sa[3]) + (R.sb[1] + R.sb[3]) + (R.sc[1] + R.sc[3]) + (R.sd[1] + R.sd[3]);
;             const float mean = s1 * (1.0f / 512.0f);
;             const float var = fmaxf(s2 * (1.0f / 512.0f) - mean * mean, 0.f);
;             const float rstd = __builtin_amdgcn_rsqf(var + EPS);
;             const float* gp = gsg + h * 64 + dc; const float* bp = bsg + h * 64 + dc;
; #pragma unroll
;             for (int i = 0; i < 8; ++i) {
;                 const unsigned w = i < 4 ? R.v0[i] : R.v1[i - 4];
;                 const float x0 = (bflo(w) - mean) * rstd * gp[2 * i] + bp[2 * i], x1 = (bfhi(w) - mean) * rstd * gp[2 * i + 1] + bp[2 * i + 1];
;                 T[(dc + 2 * i) * GT_PITCH + q] = (bf16)f2bf(x0); T[(dc + 2 * i + 1) * GT_PITCH + q] = (bf16)f2bf(x1);
;             }
;         }
.LBB0_45:
	s_and_b32 s22, s3, 7
	s_lshl_b32 s72, s22, 8
	v_add_f32_e32 v82, v28, v30
	v_add_f32_e32 v83, v24, v26
	v_add_f32_e32 v88, v29, v31
	v_add_f32_e32 v89, v25, v27
	v_add_f32_e32 v86, v20, v22
	v_add_f32_e32 v90, v21, v23
	v_add_f32_e32 v82, v83, v82
	v_add_f32_e32 v83, v89, v88
	v_add_f32_e32 v87, v16, v18
	v_add_f32_e32 v91, v17, v19
	v_add_f32_e32 v82, v86, v82
	v_add_f32_e32 v83, v90, v83
	v_add_f32_e32 v90, v87, v82
	v_add_f32_e32 v91, v91, v83
	s_nop 0
	v_mul_f32_e32 v115, 0x3b000000, v90
	s_lshl_b32 s19, s22, 6
	v_mul_f32_e32 v115, v115, v115
	s_mov_b32 s22, 0x3b000000
	v_fma_f32 v91, v91, s22, -v115
	v_max_f32_e32 v91, 0, v91
	v_add_f32_e32 v91, 0x358637bd, v91
	v_rsq_f32_e32 v91, v91
	v_lshlrev_b32_e32 v92, 16, v36
	v_lshlrev_b32_e32 v94, 16, v37
	v_lshlrev_b32_e32 v96, 16, v38
	v_and_b32_e32 v93, 0xffff0000, v36
	v_and_b32_e32 v95, 0xffff0000, v37
	v_and_b32_e32 v97, 0xffff0000, v38
	v_fmac_f32_e32 v92, 0xbb000000, v90
	v_fmac_f32_e32 v94, 0xbb000000, v90
	v_fmac_f32_e32 v96, 0xbb000000, v90
	v_lshlrev_b32_e32 v98, 16, v39
	v_fmac_f32_e32 v93, 0xbb000000, v90
	v_fmac_f32_e32 v95, 0xbb000000, v90
	v_fmac_f32_e32 v97, 0xbb000000, v90
	v_mul_f32_e32 v88, v92, v91
	v_mul_f32_e32 v92, v94, v91
	v_mul_f32_e32 v94, v96, v91
	v_fmac_f32_e32 v98, 0xbb000000, v90
	v_mul_f32_e32 v89, v93, v91
	v_mul_f32_e32 v93, v95, v91
	v_mul_f32_e32 v95, v97, v91
	v_and_b32_e32 v99, 0xffff0000, v39
	v_mul_f32_e32 v96, v98, v91
	v_fmac_f32_e32 v99, 0xbb000000, v90
	v_mul_f32_e32 v97, v99, v91
	s_mov_b32 s13, s3
	v_fma_f32 v68, v88, v218, v234
	v_fma_f32 v69, v89, v219, v235
	v_fma_f32 v12, v94, v222, v238
	v_fma_f32 v70, v92, v220, v236
	v_fma_f32 v71, v93, v221, v237
	v_fma_f32 v13, v95, v223, v239
	v_bfe_u32 v72, v68, 16, 1
	v_bfe_u32 v76, v12, 16, 1
	v_fma_f32 v14, v96, v224, v240
	v_bfe_u32 v73, v69, 16, 1
	v_bfe_u32 v74, v70, 16, 1
	v_bfe_u32 v75, v71, 16, 1
	v_bfe_u32 v77, v13, 16, 1
	v_add3_u32 v68, v68, v72, s56
	v_add3_u32 v12, v12, v76, s56
	v_add3_u32 v69, v69, v73, s56
	v_add3_u32 v70, v70, v74, s56
	v_add3_u32 v71, v71, v75, s56
	v_add3_u32 v13, v13, v77, s56
	ds_write_b16_d16_hi v134, v68
	ds_write_b16_d16_hi v135, v69 offset:272
	ds_write_b16_d16_hi v134, v70 offset:544
	ds_write_b16_d16_hi v135, v71 offset:816
	ds_write_b16_d16_hi v134, v12 offset:1088
	ds_write_b16_d16_hi v135, v13 offset:1360
	v_bfe_u32 v12, v14, 16, 1
	v_fma_f32 v15, v97, v225, v241
	v_add3_u32 v12, v14, v12, s56
	ds_write_b16_d16_hi v134, v12 offset:1632
	v_bfe_u32 v12, v15, 16, 1
	v_add3_u32 v12, v15, v12, s56
	ds_write_b16_d16_hi v135, v12 offset:1904
	v_lshlrev_b32_e32 v12, 16, v32
	v_fmac_f32_e32 v12, 0xbb000000, v90
	v_mul_f32_e32 v12, v12, v91
	v_fma_f32 v4, v12, v226, v242
	v_and_b32_e32 v8, 0xffff0000, v32
	v_fmac_f32_e32 v8, 0xbb000000, v90
	v_mul_f32_e32 v8, v8, v91
	v_fma_f32 v5, v8, v227, v243
	v_bfe_u32 v8, v4, 16, 1
	v_add3_u32 v4, v4, v8, s56
	ds_write_b16_d16_hi v134, v4 offset:2176
	v_bfe_u32 v4, v5, 16, 1
	v_add3_u32 v4, v5, v4, s56
	ds_write_b16_d16_hi v135, v4 offset:2448
	v_lshlrev_b32_e32 v4, 16, v33
	v_fmac_f32_e32 v4, 0xbb000000, v90
	v_and_b32_e32 v5, 0xffff0000, v33
	v_mul_f32_e32 v4, v4, v91
	v_fmac_f32_e32 v5, 0xbb000000, v90
	v_fma_f32 v4, v4, v228, v244
	v_mul_f32_e32 v5, v5, v91
	v_fma_f32 v7, v5, v229, v245
	v_bfe_u32 v5, v4, 16, 1
	v_add3_u32 v4, v4, v5, s56
	ds_write_b16_d16_hi v134, v4 offset:2720
	v_bfe_u32 v4, v7, 16, 1
	v_add3_u32 v4, v7, v4, s56
	ds_write_b16_d16_hi v135, v4 offset:2992
	v_lshlrev_b32_e32 v4, 16, v34
	v_fmac_f32_e32 v4, 0xbb000000, v90
	v_mul_f32_e32 v4, v4, v91
	v_and_b32_e32 v5, 0xffff0000, v34
	v_fma_f32 v4, v4, v230, v246
	v_fmac_f32_e32 v5, 0xbb000000, v90
	v_mul_f32_e32 v5, v5, v91
	v_bfe_u32 v6, v4, 16, 1
	v_fma_f32 v5, v5, v231, v247
	v_add3_u32 v4, v4, v6, s56
	ds_write_b16_d16_hi v134, v4 offset:3264
	v_bfe_u32 v4, v5, 16, 1
	v_add3_u32 v4, v5, v4, s56
	ds_write_b16_d16_hi v135, v4 offset:3536
	v_lshlrev_b32_e32 v4, 16, v35
	v_fmac_f32_e32 v4, 0xbb000000, v90
	v_and_b32_e32 v5, 0xffff0000, v35
	v_mul_f32_e32 v4, v4, v91
	v_fmac_f32_e32 v5, 0xbb000000, v90
	v_fma_f32 v4, v4, v232, v248
	v_mul_f32_e32 v5, v5, v91
	v_fma_f32 v87, v5, v233, v249
	v_bfe_u32 v5, v4, 16, 1
	v_add3_u32 v4, v4, v5, s56
	ds_write_b16_d16_hi v134, v4 offset:3808
	v_bfe_u32 v4, v87, 16, 1
	v_add3_u32 v4, v87, v4, s56
	ds_write_b16_d16_hi v135, v4 offset:4080
	s_branch .LBB0_47

; __device__ __forceinline__ void gate_phase(int bx, int G, bool skip_ctx, const bf16* __restrict__ VG, const bf16* __restrict__ U, const float* __restrict__ stats, ...
;     ...
;         u32x2 ucur[4]; bf16x8 wcur[8];
; #pragma unroll
;         for (int g4 = 0; g4 < 4; ++g4) ucur[g4] = R.uu[g4];
; #pragma unroll
;         for (int ks = 0; ks < 8; ++ks) wcur[ks] = R.wf[ks];
;         const float bias = bsl[h * 128 + p];
;         const int un = next_unit(u);
;         if (un < NU) GATE_LOAD(un);
.LBB0_49:
	v_mov_b64_e32 v[70:71], v[2:3]
	v_mov_b64_e32 v[74:75], v[62:63]
	v_mov_b64_e32 v[78:79], v[66:67]
	v_mov_b64_e32 v[82:83], v[54:55]
	v_mov_b64_e32 v[86:87], v[58:59]
	v_mov_b64_e32 v[90:91], v[50:51]
	v_mov_b64_e32 v[94:95], v[46:47]
	v_mov_b64_e32 v[98:99], v[42:43]
	s_mov_b64 s[22:23], 0
	s_andn2_b64 vcc, exec, s[38:39]
	v_mov_b64_e32 v[126:127], v[124:125]
	v_mov_b64_e32 v[128:129], v[122:123]
	v_mov_b64_e32 v[130:131], v[120:121]
	v_mov_b64_e32 v[132:133], v[106:107]
	v_mov_b64_e32 v[68:69], v[0:1]
	v_mov_b64_e32 v[72:73], v[60:61]
	v_mov_b64_e32 v[76:77], v[64:65]
	v_mov_b64_e32 v[80:81], v[52:53]
	v_mov_b64_e32 v[84:85], v[56:57]
	v_mov_b64_e32 v[88:89], v[48:49]
	v_mov_b64_e32 v[92:93], v[44:45]
	v_mov_b64_e32 v[96:97], v[40:41]
	s_cbranch_vccz .LBB0_44
	s_waitcnt vmcnt(4)
	v_mov_b64_e32 v[16:17], v[172:173]
	v_mov_b64_e32 v[18:19], v[174:175]
	v_mov_b64_e32 v[20:21], v[176:177]
	v_mov_b64_e32 v[22:23], v[178:179]
	v_mov_b64_e32 v[24:25], v[180:181]
	v_mov_b64_e32 v[26:27], v[182:183]
	v_mov_b64_e32 v[28:29], v[184:185]
	v_mov_b64_e32 v[30:31], v[186:187]
	v_mov_b64_e32 v[32:33], v[188:189]
	v_mov_b64_e32 v[34:35], v[190:191]
	v_mov_b64_e32 v[36:37], v[192:193]
	v_mov_b64_e32 v[38:39], v[194:195]
	v_mov_b64_e32 v[126:127], v[196:197]
	v_mov_b64_e32 v[128:129], v[198:199]
	v_mov_b64_e32 v[130:131], v[164:165]
	v_mov_b64_e32 v[132:133], v[166:167]
	s_add_i32 s37, s3, s24

.Lgate_n2_ok:
	s_ashr_i32 s27, s26, 31
	s_lshl_b64 s[22:23], s[26:27], 7
	v_lshl_add_u64 v[4:5], s[22:23], 0, v[100:101]
	s_and_b32 s25, s37, 7
	v_lshlrev_b64 v[6:7], 6, v[4:5]
	v_lshlrev_b64 v[4:5], 10, v[4:5]
	v_lshl_add_u64 v[4:5], s[10:11], 0, v[4:5]
	s_lshl_b32 s72, s25, 7
	v_lshl_add_u64 v[4:5], v[4:5], 0, s[72:73]
	v_mov_b32_e32 v115, v161
	v_lshl_add_u64 v[6:7], s[40:41], 0, v[6:7]
	v_lshl_add_u64 v[4:5], v[4:5], 0, v[114:115]
	global_load_dwordx4 v[172:175], v[6:7], off offset:48
	global_load_dwordx4 v[176:179], v[6:7], off offset:32
	global_load_dwordx4 v[180:183], v[6:7], off offset:16
	global_load_dwordx4 v[184:187], v[6:7], off
	global_load_dwordx4 v[188:191], v[4:5], off offset:16 nt
	global_load_dwordx4 v[192:195], v[4:5], off nt
	v_lshl_add_u64 v[4:5], s[22:23], 0, v[102:103]
	v_lshlrev_b64 v[4:5], 10, v[4:5]
	v_lshl_add_u64 v[4:5], s[8:9], 0, v[4:5]
	v_lshl_add_u64 v[4:5], v[4:5], 0, s[72:73]
	v_mov_b32_e32 v117, v161
	v_lshl_add_u64 v[4:5], v[4:5], 0, v[116:117]
	v_mov_b32_e32 v119, v161
	v_lshl_add_u64 v[4:5], v[4:5], 0, v[118:119]
	global_load_dwordx2 v[196:197], v[4:5], off nt
	global_load_dwordx2 v[198:199], v[4:5], off offset:16 nt
	global_load_dwordx2 v[164:165], v[4:5], off offset:32 nt
	global_load_dwordx2 v[166:167], v[4:5], off offset:48 nt
.Lgate_n2_none:
	s_mov_b64 s[22:23], -1
	s_branch .LBB0_44
